# v072 stack + gate/up and down GEMM: first K-iteration peeled with C=0 first-touch MFMAs, accumulator re-zeroing moves removed
# speedup vs baseline: 1.0057x; 1.0012x over previous
.LBB0_1247:
	s_ashr_i32 s13, s12, 31
	s_lshl_b64 s[14:15], s[12:13], 19
	s_add_u32 s14, s26, s14
	s_addc_u32 s15, s27, s15
	s_and_b64 s[16:17], s[8:9], exec
	s_cselect_b32 s13, s15, s21
	s_cselect_b32 s19, s14, s20
	s_ashr_i32 s11, s10, 31
	s_lshl_b64 s[16:17], s[10:11], 19
	s_add_u32 s16, s28, s16
	s_addc_u32 s17, s29, s17
	s_and_b64 s[24:25], s[8:9], exec
	s_cselect_b32 s11, s17, s23
	s_cselect_b32 s44, s16, s22
	s_add_u32 s20, s20, 0x40080
	s_addc_u32 s21, s21, 0
	s_add_u32 s45, s22, 0x100
	s_addc_u32 s46, s23, 0
	s_mov_b32 s47, -2
	s_waitcnt vmcnt(0)
	s_add_u32 s22, s20, 0xfffc0080
	s_addc_u32 s23, s21, -1
	s_add_i32 s48, 0, 0x10000
	s_cmp_eq_u32 s47, 12
	s_cselect_b32 s25, s13, s23
	s_cselect_b32 s24, s19, s22
	s_cselect_b32 s23, s11, s46
	s_cselect_b32 s22, s44, s45
	s_add_i32 s50, 0, 0x14000
	v_add_u32_e32 v142, s48, v171
	v_add_u32_e32 v164, s50, v171
	ds_read_b128 v[130:133], v142
	ds_read_b128 v[134:137], v142 offset:1024
	ds_read_b128 v[138:141], v142 offset:2048
	ds_read_b128 v[142:145], v142 offset:3072
	ds_read_b128 v[160:163], v164
	ds_read_b128 v[176:179], v164 offset:1024
	ds_read_b128 v[180:183], v164 offset:2048
	ds_read_b128 v[184:187], v164 offset:3072
	v_lshl_add_u64 v[164:165], s[20:21], 0, v[156:157]
	s_add_i32 m0, s31, 0xc000
	ds_read_b128 v[188:191], v175
	ds_read_b128 v[192:195], v175 offset:1024
	ds_read_b128 v[196:199], v175 offset:2048
	ds_read_b128 v[200:203], v175 offset:3072
	ds_read_b128 v[204:207], v175 offset:4096
	ds_read_b128 v[208:211], v175 offset:5120
	ds_read_b128 v[212:215], v175 offset:6144
	ds_read_b128 v[216:219], v175 offset:7168
	global_load_lds_dwordx4 v[164:165], off
	v_lshl_add_u64 v[164:165], s[20:21], 0, v[158:159]
	s_add_i32 m0, s31, 0xe000
	s_nop 0
	global_load_lds_dwordx4 v[164:165], off
	s_waitcnt vmcnt(8)
	s_waitcnt lgkmcnt(0)
	s_barrier
	s_setprio 1
	v_mfma_f32_16x16x32_bf16 v[126:129], v[130:133], v[188:191], 0
	v_mfma_f32_16x16x32_bf16 v[122:125], v[138:141], v[188:191], 0
	v_mfma_f32_16x16x32_bf16 v[110:113], v[130:133], v[196:199], 0
	v_mfma_f32_16x16x32_bf16 v[106:109], v[138:141], v[196:199], 0
	v_mfma_f32_16x16x32_bf16 v[94:97], v[130:133], v[204:207], 0
	v_mfma_f32_16x16x32_bf16 v[90:93], v[138:141], v[204:207], 0
	v_mfma_f32_16x16x32_bf16 v[78:81], v[130:133], v[212:215], 0
	v_mfma_f32_16x16x32_bf16 v[74:77], v[138:141], v[212:215], 0
	v_mfma_f32_16x16x32_bf16 v[126:129], v[134:137], v[192:195], v[126:129]
	v_mfma_f32_16x16x32_bf16 v[122:125], v[142:145], v[192:195], v[122:125]
	v_mfma_f32_16x16x32_bf16 v[110:113], v[134:137], v[200:203], v[110:113]
	v_mfma_f32_16x16x32_bf16 v[106:109], v[142:145], v[200:203], v[106:109]
	v_mfma_f32_16x16x32_bf16 v[94:97], v[134:137], v[208:211], v[94:97]
	v_mfma_f32_16x16x32_bf16 v[90:93], v[142:145], v[208:211], v[90:93]
	v_mfma_f32_16x16x32_bf16 v[78:81], v[134:137], v[216:219], v[78:81]
	v_mfma_f32_16x16x32_bf16 v[74:77], v[142:145], v[216:219], v[74:77]
	v_mfma_f32_16x16x32_bf16 v[118:121], v[160:163], v[188:191], 0
	v_mfma_f32_16x16x32_bf16 v[114:117], v[180:183], v[188:191], 0
	v_mfma_f32_16x16x32_bf16 v[102:105], v[160:163], v[196:199], 0
	v_mfma_f32_16x16x32_bf16 v[98:101], v[180:183], v[196:199], 0
	v_mfma_f32_16x16x32_bf16 v[86:89], v[160:163], v[204:207], 0
	v_mfma_f32_16x16x32_bf16 v[82:85], v[180:183], v[204:207], 0
	v_mfma_f32_16x16x32_bf16 v[70:73], v[160:163], v[212:215], 0
	v_mfma_f32_16x16x32_bf16 v[66:69], v[180:183], v[212:215], 0
	v_mfma_f32_16x16x32_bf16 v[118:121], v[176:179], v[192:195], v[118:121]
	v_mfma_f32_16x16x32_bf16 v[114:117], v[184:187], v[192:195], v[114:117]
	v_mfma_f32_16x16x32_bf16 v[102:105], v[176:179], v[200:203], v[102:105]
	v_mfma_f32_16x16x32_bf16 v[98:101], v[184:187], v[200:203], v[98:101]
	v_mfma_f32_16x16x32_bf16 v[86:89], v[176:179], v[208:211], v[86:89]
	v_mfma_f32_16x16x32_bf16 v[82:85], v[184:187], v[208:211], v[82:85]
	v_mfma_f32_16x16x32_bf16 v[70:73], v[176:179], v[216:219], v[70:73]
	v_mfma_f32_16x16x32_bf16 v[66:69], v[184:187], v[216:219], v[66:69]
	s_setprio 0
	s_barrier
	s_add_i32 s48, s48, s30
	v_lshl_add_u64 v[164:165], s[22:23], 0, v[0:1]
	s_mov_b32 m0, s48
	ds_read_b128 v[188:191], v175 offset:16384
	ds_read_b128 v[192:195], v175 offset:17408
	ds_read_b128 v[196:199], v175 offset:18432
	ds_read_b128 v[200:203], v175 offset:19456
	ds_read_b128 v[204:207], v175 offset:20480
	ds_read_b128 v[208:211], v175 offset:21504
	ds_read_b128 v[212:215], v175 offset:22528
	ds_read_b128 v[216:219], v175 offset:23552
	global_load_lds_dwordx4 v[164:165], off
	s_add_i32 m0, s48, 0x2000
	s_add_u32 s48, s22, 0x40000
	v_lshl_add_u64 v[168:169], s[22:23], 0, v[146:147]
	s_addc_u32 s49, s23, 0
	s_add_i32 s50, s50, s30
	global_load_lds_dwordx4 v[168:169], off
	v_lshl_add_u64 v[172:173], s[48:49], 0, v[0:1]
	s_mov_b32 m0, s50
	v_lshl_add_u64 v[220:221], s[24:25], 0, v[148:149]
	global_load_lds_dwordx4 v[172:173], off
	v_lshl_add_u64 v[172:173], s[48:49], 0, v[146:147]
	s_add_i32 m0, s50, 0x2000
	s_nop 0
	global_load_lds_dwordx4 v[172:173], off
	v_lshl_add_u64 v[172:173], s[24:25], 0, v[150:151]
	s_mov_b32 m0, s31
	s_nop 0
	global_load_lds_dwordx4 v[172:173], off
	s_mov_b32 m0, s33
	s_nop 0
	global_load_lds_dwordx4 v[220:221], off
	s_waitcnt vmcnt(8)
	s_waitcnt lgkmcnt(0)
	s_barrier
	s_setprio 1
	v_mfma_f32_16x16x32_bf16 v[62:65], v[130:133], v[188:191], 0
	v_mfma_f32_16x16x32_bf16 v[58:61], v[138:141], v[188:191], 0
	v_mfma_f32_16x16x32_bf16 v[46:49], v[130:133], v[196:199], 0
	v_mfma_f32_16x16x32_bf16 v[42:45], v[138:141], v[196:199], 0
	v_mfma_f32_16x16x32_bf16 v[30:33], v[130:133], v[204:207], 0
	v_mfma_f32_16x16x32_bf16 v[26:29], v[138:141], v[204:207], 0
	v_mfma_f32_16x16x32_bf16 v[14:17], v[130:133], v[212:215], 0
	v_mfma_f32_16x16x32_bf16 v[10:13], v[138:141], v[212:215], 0
	v_mfma_f32_16x16x32_bf16 v[62:65], v[134:137], v[192:195], v[62:65]
	v_mfma_f32_16x16x32_bf16 v[58:61], v[142:145], v[192:195], v[58:61]
	v_mfma_f32_16x16x32_bf16 v[46:49], v[134:137], v[200:203], v[46:49]
	v_mfma_f32_16x16x32_bf16 v[42:45], v[142:145], v[200:203], v[42:45]
	v_mfma_f32_16x16x32_bf16 v[30:33], v[134:137], v[208:211], v[30:33]
	v_mfma_f32_16x16x32_bf16 v[26:29], v[142:145], v[208:211], v[26:29]
	v_mfma_f32_16x16x32_bf16 v[14:17], v[134:137], v[216:219], v[14:17]
	v_mfma_f32_16x16x32_bf16 v[10:13], v[142:145], v[216:219], v[10:13]
	v_mfma_f32_16x16x32_bf16 v[54:57], v[160:163], v[188:191], 0
	v_mfma_f32_16x16x32_bf16 v[50:53], v[180:183], v[188:191], 0
	v_mfma_f32_16x16x32_bf16 v[38:41], v[160:163], v[196:199], 0
	v_mfma_f32_16x16x32_bf16 v[34:37], v[180:183], v[196:199], 0
	v_mfma_f32_16x16x32_bf16 v[22:25], v[160:163], v[204:207], 0
	v_mfma_f32_16x16x32_bf16 v[18:21], v[180:183], v[204:207], 0
	v_mfma_f32_16x16x32_bf16 v[6:9], v[160:163], v[212:215], 0
	v_mfma_f32_16x16x32_bf16 v[2:5], v[180:183], v[212:215], 0
	v_mfma_f32_16x16x32_bf16 v[54:57], v[176:179], v[192:195], v[54:57]
	v_mfma_f32_16x16x32_bf16 v[50:53], v[184:187], v[192:195], v[50:53]
	v_mfma_f32_16x16x32_bf16 v[38:41], v[176:179], v[200:203], v[38:41]
	v_mfma_f32_16x16x32_bf16 v[34:37], v[184:187], v[200:203], v[34:37]
	v_mfma_f32_16x16x32_bf16 v[22:25], v[176:179], v[208:211], v[22:25]
	v_mfma_f32_16x16x32_bf16 v[18:21], v[184:187], v[208:211], v[18:21]
	v_mfma_f32_16x16x32_bf16 v[6:9], v[176:179], v[216:219], v[6:9]
	v_mfma_f32_16x16x32_bf16 v[2:5], v[184:187], v[216:219], v[2:5]
	s_setprio 0
	s_barrier
	s_add_i32 s48, 0, 0x18000
	s_add_i32 s49, 0, 0x1c000
	v_add_u32_e32 v142, s48, v171
	v_add_u32_e32 v166, s49, v171
	ds_read_b128 v[130:133], v142
	ds_read_b128 v[134:137], v142 offset:1024
	ds_read_b128 v[138:141], v142 offset:2048
	ds_read_b128 v[142:145], v142 offset:3072
	ds_read_b128 v[160:163], v166
	ds_read_b128 v[176:179], v166 offset:1024
	ds_read_b128 v[180:183], v166 offset:2048
	ds_read_b128 v[184:187], v166 offset:3072
	s_add_u32 s24, s24, 0x40000
	s_addc_u32 s25, s25, 0
	s_mov_b32 m0, s34
	v_lshl_add_u64 v[222:223], s[24:25], 0, v[150:151]
	ds_read_b128 v[188:191], v175 offset:32768
	ds_read_b128 v[192:195], v175 offset:33792
	ds_read_b128 v[196:199], v175 offset:34816
	ds_read_b128 v[200:203], v175 offset:35840
	ds_read_b128 v[204:207], v175 offset:36864
	ds_read_b128 v[208:211], v175 offset:37888
	ds_read_b128 v[212:215], v175 offset:38912
	ds_read_b128 v[216:219], v175 offset:39936
	global_load_lds_dwordx4 v[222:223], off
	v_lshl_add_u64 v[222:223], s[24:25], 0, v[148:149]
	s_mov_b32 m0, s35
	s_nop 0
	global_load_lds_dwordx4 v[222:223], off
	s_waitcnt vmcnt(8)
	s_waitcnt lgkmcnt(0)
	s_barrier
	s_setprio 1
	v_mfma_f32_16x16x32_bf16 v[126:129], v[130:133], v[188:191], v[126:129]
	v_mfma_f32_16x16x32_bf16 v[122:125], v[138:141], v[188:191], v[122:125]
	v_mfma_f32_16x16x32_bf16 v[110:113], v[130:133], v[196:199], v[110:113]
	v_mfma_f32_16x16x32_bf16 v[106:109], v[138:141], v[196:199], v[106:109]
	v_mfma_f32_16x16x32_bf16 v[94:97], v[130:133], v[204:207], v[94:97]
	v_mfma_f32_16x16x32_bf16 v[90:93], v[138:141], v[204:207], v[90:93]
	v_mfma_f32_16x16x32_bf16 v[78:81], v[130:133], v[212:215], v[78:81]
	v_mfma_f32_16x16x32_bf16 v[74:77], v[138:141], v[212:215], v[74:77]
	v_mfma_f32_16x16x32_bf16 v[126:129], v[134:137], v[192:195], v[126:129]
	v_mfma_f32_16x16x32_bf16 v[122:125], v[142:145], v[192:195], v[122:125]
	v_mfma_f32_16x16x32_bf16 v[110:113], v[134:137], v[200:203], v[110:113]
	v_mfma_f32_16x16x32_bf16 v[106:109], v[142:145], v[200:203], v[106:109]
	v_mfma_f32_16x16x32_bf16 v[94:97], v[134:137], v[208:211], v[94:97]
	v_mfma_f32_16x16x32_bf16 v[90:93], v[142:145], v[208:211], v[90:93]
	v_mfma_f32_16x16x32_bf16 v[78:81], v[134:137], v[216:219], v[78:81]
	v_mfma_f32_16x16x32_bf16 v[74:77], v[142:145], v[216:219], v[74:77]
	v_mfma_f32_16x16x32_bf16 v[118:121], v[160:163], v[188:191], v[118:121]
	v_mfma_f32_16x16x32_bf16 v[114:117], v[180:183], v[188:191], v[114:117]
	v_mfma_f32_16x16x32_bf16 v[102:105], v[160:163], v[196:199], v[102:105]
	v_mfma_f32_16x16x32_bf16 v[98:101], v[180:183], v[196:199], v[98:101]
	v_mfma_f32_16x16x32_bf16 v[86:89], v[160:163], v[204:207], v[86:89]
	v_mfma_f32_16x16x32_bf16 v[82:85], v[180:183], v[204:207], v[82:85]
	v_mfma_f32_16x16x32_bf16 v[70:73], v[160:163], v[212:215], v[70:73]
	v_mfma_f32_16x16x32_bf16 v[66:69], v[180:183], v[212:215], v[66:69]
	v_mfma_f32_16x16x32_bf16 v[118:121], v[176:179], v[192:195], v[118:121]
	v_mfma_f32_16x16x32_bf16 v[114:117], v[184:187], v[192:195], v[114:117]
	v_mfma_f32_16x16x32_bf16 v[102:105], v[176:179], v[200:203], v[102:105]
	v_mfma_f32_16x16x32_bf16 v[98:101], v[184:187], v[200:203], v[98:101]
	v_mfma_f32_16x16x32_bf16 v[86:89], v[176:179], v[208:211], v[86:89]
	v_mfma_f32_16x16x32_bf16 v[82:85], v[184:187], v[208:211], v[82:85]
	v_mfma_f32_16x16x32_bf16 v[70:73], v[176:179], v[216:219], v[70:73]
	v_mfma_f32_16x16x32_bf16 v[66:69], v[184:187], v[216:219], v[66:69]
	s_setprio 0
	s_barrier
	s_add_i32 s24, s48, s30
	v_lshl_add_u64 v[164:165], v[164:165], 0, s[80:81]
	s_mov_b32 m0, s24
	ds_read_b128 v[188:191], v175 offset:49152
	ds_read_b128 v[192:195], v175 offset:50176
	ds_read_b128 v[196:199], v175 offset:51200
	ds_read_b128 v[200:203], v175 offset:52224
	ds_read_b128 v[204:207], v175 offset:53248
	ds_read_b128 v[208:211], v175 offset:54272
	ds_read_b128 v[212:215], v175 offset:55296
	ds_read_b128 v[216:219], v175 offset:56320
	global_load_lds_dwordx4 v[164:165], off
	s_add_i32 m0, s24, 0x2000
	s_add_u32 s22, s22, 0x40080
	v_lshl_add_u64 v[164:165], v[168:169], 0, s[80:81]
	s_addc_u32 s23, s23, 0
	s_add_i32 s24, s49, s30
	global_load_lds_dwordx4 v[164:165], off
	v_lshl_add_u64 v[164:165], s[22:23], 0, v[0:1]
	s_mov_b32 m0, s24
	s_nop 0
	global_load_lds_dwordx4 v[164:165], off
	v_lshl_add_u64 v[164:165], s[22:23], 0, v[146:147]
	s_add_i32 m0, s24, 0x2000
	s_nop 0
	global_load_lds_dwordx4 v[164:165], off
	v_lshl_add_u64 v[164:165], v[172:173], 0, s[80:81]
	s_mov_b32 m0, s41
	s_nop 0
	global_load_lds_dwordx4 v[164:165], off
	v_lshl_add_u64 v[164:165], v[220:221], 0, s[80:81]
	s_mov_b32 m0, s42
	s_nop 0
	global_load_lds_dwordx4 v[164:165], off
	s_waitcnt vmcnt(8)
	s_waitcnt lgkmcnt(0)
	s_barrier
	s_setprio 1
	v_mfma_f32_16x16x32_bf16 v[62:65], v[130:133], v[188:191], v[62:65]
	v_mfma_f32_16x16x32_bf16 v[58:61], v[138:141], v[188:191], v[58:61]
	v_mfma_f32_16x16x32_bf16 v[46:49], v[130:133], v[196:199], v[46:49]
	v_mfma_f32_16x16x32_bf16 v[42:45], v[138:141], v[196:199], v[42:45]
	v_mfma_f32_16x16x32_bf16 v[30:33], v[130:133], v[204:207], v[30:33]
	v_mfma_f32_16x16x32_bf16 v[26:29], v[138:141], v[204:207], v[26:29]
	v_mfma_f32_16x16x32_bf16 v[14:17], v[130:133], v[212:215], v[14:17]
	v_mfma_f32_16x16x32_bf16 v[10:13], v[138:141], v[212:215], v[10:13]
	v_mfma_f32_16x16x32_bf16 v[62:65], v[134:137], v[192:195], v[62:65]
	v_mfma_f32_16x16x32_bf16 v[58:61], v[142:145], v[192:195], v[58:61]
	v_mfma_f32_16x16x32_bf16 v[46:49], v[134:137], v[200:203], v[46:49]
	v_mfma_f32_16x16x32_bf16 v[42:45], v[142:145], v[200:203], v[42:45]
	v_mfma_f32_16x16x32_bf16 v[30:33], v[134:137], v[208:211], v[30:33]
	v_mfma_f32_16x16x32_bf16 v[26:29], v[142:145], v[208:211], v[26:29]
	v_mfma_f32_16x16x32_bf16 v[14:17], v[134:137], v[216:219], v[14:17]
	v_mfma_f32_16x16x32_bf16 v[10:13], v[142:145], v[216:219], v[10:13]
	v_mfma_f32_16x16x32_bf16 v[54:57], v[160:163], v[188:191], v[54:57]
	v_mfma_f32_16x16x32_bf16 v[50:53], v[180:183], v[188:191], v[50:53]
	v_mfma_f32_16x16x32_bf16 v[38:41], v[160:163], v[196:199], v[38:41]
	v_mfma_f32_16x16x32_bf16 v[34:37], v[180:183], v[196:199], v[34:37]
	v_mfma_f32_16x16x32_bf16 v[22:25], v[160:163], v[204:207], v[22:25]
	v_mfma_f32_16x16x32_bf16 v[18:21], v[180:183], v[204:207], v[18:21]
	v_mfma_f32_16x16x32_bf16 v[6:9], v[160:163], v[212:215], v[6:9]
	v_mfma_f32_16x16x32_bf16 v[2:5], v[180:183], v[212:215], v[2:5]
	v_mfma_f32_16x16x32_bf16 v[54:57], v[176:179], v[192:195], v[54:57]
	v_mfma_f32_16x16x32_bf16 v[50:53], v[184:187], v[192:195], v[50:53]
	v_mfma_f32_16x16x32_bf16 v[38:41], v[176:179], v[200:203], v[38:41]
	v_mfma_f32_16x16x32_bf16 v[34:37], v[184:187], v[200:203], v[34:37]
	v_mfma_f32_16x16x32_bf16 v[22:25], v[176:179], v[208:211], v[22:25]
	v_mfma_f32_16x16x32_bf16 v[18:21], v[184:187], v[208:211], v[18:21]
	v_mfma_f32_16x16x32_bf16 v[6:9], v[176:179], v[216:219], v[6:9]
	v_mfma_f32_16x16x32_bf16 v[2:5], v[184:187], v[216:219], v[2:5]
	s_setprio 0
	s_barrier
	s_add_i32 s47, s47, 2
	s_add_u32 s20, s20, 0x100
	s_addc_u32 s21, s21, 0
	s_add_u32 s45, s45, 0x100
	s_addc_u32 s46, s46, 0
	s_cmp_gt_u32 s47, 13

.LBB0_1440:
	s_add_u32 s66, s30, 0x100
	s_addc_u32 s67, s31, 0
	s_mov_b32 s68, -2
	s_waitcnt vmcnt(0)
	s_add_u32 s30, s6, 0x100
	s_addc_u32 s31, s7, 0
	s_add_i32 s70, 0, 0x10000
	s_cmp_eq_u32 s68, 40
	s_cselect_b32 s41, s27, s31
	s_cselect_b32 s40, s26, s30
	s_cselect_b32 s39, s29, s67
	s_cselect_b32 s38, s28, s66
	s_add_i32 s71, 0, 0x14000
	v_add_u32_e32 v78, s70, v203
	v_add_u32_e32 v158, s71, v203
	ds_read_b128 v[66:69], v78
	ds_read_b128 v[70:73], v78 offset:1024
	ds_read_b128 v[74:77], v78 offset:2048
	ds_read_b128 v[78:81], v78 offset:3072
	ds_read_b128 v[146:149], v158
	ds_read_b128 v[150:153], v158 offset:1024
	ds_read_b128 v[154:157], v158 offset:2048
	ds_read_b128 v[158:161], v158 offset:3072
	v_lshl_add_u64 v[200:201], s[6:7], 0, v[172:173]
	s_add_i32 m0, s33, 0xc000
	ds_read_b128 v[162:165], v205
	ds_read_b128 v[176:179], v205 offset:1024
	ds_read_b128 v[180:183], v205 offset:2048
	ds_read_b128 v[184:187], v205 offset:3072
	ds_read_b128 v[188:191], v205 offset:4096
	ds_read_b128 v[192:195], v205 offset:5120
	ds_read_b128 v[196:199], v205 offset:6144
	ds_read_b128 v[206:209], v205 offset:7168
	global_load_lds_dwordx4 v[200:201], off
	v_lshl_add_u64 v[200:201], s[6:7], 0, v[174:175]
	s_add_i32 m0, s33, 0xe000
	s_nop 0
	global_load_lds_dwordx4 v[200:201], off
	s_waitcnt vmcnt(8)
	s_waitcnt lgkmcnt(0)
	s_barrier
	s_setprio 1
	v_mfma_f32_16x16x32_bf16 v[142:145], v[66:69], v[162:165], 0
	v_mfma_f32_16x16x32_bf16 v[138:141], v[74:77], v[162:165], 0
	v_mfma_f32_16x16x32_bf16 v[126:129], v[66:69], v[180:183], 0
	v_mfma_f32_16x16x32_bf16 v[122:125], v[74:77], v[180:183], 0
	v_mfma_f32_16x16x32_bf16 v[110:113], v[66:69], v[188:191], 0
	v_mfma_f32_16x16x32_bf16 v[106:109], v[74:77], v[188:191], 0
	v_mfma_f32_16x16x32_bf16 v[94:97], v[66:69], v[196:199], 0
	v_mfma_f32_16x16x32_bf16 v[90:93], v[74:77], v[196:199], 0
	v_mfma_f32_16x16x32_bf16 v[142:145], v[70:73], v[176:179], v[142:145]
	v_mfma_f32_16x16x32_bf16 v[138:141], v[78:81], v[176:179], v[138:141]
	v_mfma_f32_16x16x32_bf16 v[126:129], v[70:73], v[184:187], v[126:129]
	v_mfma_f32_16x16x32_bf16 v[122:125], v[78:81], v[184:187], v[122:125]
	v_mfma_f32_16x16x32_bf16 v[110:113], v[70:73], v[192:195], v[110:113]
	v_mfma_f32_16x16x32_bf16 v[106:109], v[78:81], v[192:195], v[106:109]
	v_mfma_f32_16x16x32_bf16 v[94:97], v[70:73], v[206:209], v[94:97]
	v_mfma_f32_16x16x32_bf16 v[90:93], v[78:81], v[206:209], v[90:93]
	v_mfma_f32_16x16x32_bf16 v[134:137], v[146:149], v[162:165], 0
	v_mfma_f32_16x16x32_bf16 v[130:133], v[154:157], v[162:165], 0
	v_mfma_f32_16x16x32_bf16 v[118:121], v[146:149], v[180:183], 0
	v_mfma_f32_16x16x32_bf16 v[114:117], v[154:157], v[180:183], 0
	v_mfma_f32_16x16x32_bf16 v[102:105], v[146:149], v[188:191], 0
	v_mfma_f32_16x16x32_bf16 v[98:101], v[154:157], v[188:191], 0
	v_mfma_f32_16x16x32_bf16 v[86:89], v[146:149], v[196:199], 0
	v_mfma_f32_16x16x32_bf16 v[82:85], v[154:157], v[196:199], 0
	v_mfma_f32_16x16x32_bf16 v[134:137], v[150:153], v[176:179], v[134:137]
	v_mfma_f32_16x16x32_bf16 v[130:133], v[158:161], v[176:179], v[130:133]
	v_mfma_f32_16x16x32_bf16 v[118:121], v[150:153], v[184:187], v[118:121]
	v_mfma_f32_16x16x32_bf16 v[114:117], v[158:161], v[184:187], v[114:117]
	v_mfma_f32_16x16x32_bf16 v[102:105], v[150:153], v[192:195], v[102:105]
	v_mfma_f32_16x16x32_bf16 v[98:101], v[158:161], v[192:195], v[98:101]
	v_mfma_f32_16x16x32_bf16 v[86:89], v[150:153], v[206:209], v[86:89]
	v_mfma_f32_16x16x32_bf16 v[82:85], v[158:161], v[206:209], v[82:85]
	s_setprio 0
	s_barrier
	s_add_i32 s6, s70, s45
	v_lshl_add_u64 v[200:201], s[38:39], 0, v[0:1]
	s_mov_b32 m0, s6
	ds_read_b128 v[162:165], v205 offset:16384
	ds_read_b128 v[176:179], v205 offset:17408
	ds_read_b128 v[180:183], v205 offset:18432
	ds_read_b128 v[184:187], v205 offset:19456
	ds_read_b128 v[188:191], v205 offset:20480
	ds_read_b128 v[192:195], v205 offset:21504
	ds_read_b128 v[196:199], v205 offset:22528
	ds_read_b128 v[206:209], v205 offset:23552
	global_load_lds_dwordx4 v[200:201], off
	s_add_i32 m0, s6, 0x2000
	s_add_u32 s6, s38, 0xb0000
	v_lshl_add_u64 v[210:211], s[38:39], 0, v[170:171]
	s_addc_u32 s7, s39, 0
	s_add_i32 s70, s71, s45
	global_load_lds_dwordx4 v[210:211], off
	v_lshl_add_u64 v[212:213], s[6:7], 0, v[0:1]
	s_mov_b32 m0, s70
	v_lshl_add_u64 v[214:215], s[40:41], 0, v[168:169]
	global_load_lds_dwordx4 v[212:213], off
	v_lshl_add_u64 v[212:213], s[6:7], 0, v[170:171]
	s_add_i32 m0, s70, 0x2000
	s_nop 0
	global_load_lds_dwordx4 v[212:213], off
	v_lshl_add_u64 v[212:213], s[40:41], 0, v[166:167]
	s_mov_b32 m0, s33
	s_nop 0
	global_load_lds_dwordx4 v[212:213], off
	s_mov_b32 m0, s34
	s_nop 0
	global_load_lds_dwordx4 v[214:215], off
	s_waitcnt vmcnt(8)
	s_waitcnt lgkmcnt(0)
	s_barrier
	s_setprio 1
	v_mfma_f32_16x16x32_bf16 v[62:65], v[66:69], v[162:165], 0
	v_mfma_f32_16x16x32_bf16 v[58:61], v[74:77], v[162:165], 0
	v_mfma_f32_16x16x32_bf16 v[46:49], v[66:69], v[180:183], 0
	v_mfma_f32_16x16x32_bf16 v[42:45], v[74:77], v[180:183], 0
	v_mfma_f32_16x16x32_bf16 v[30:33], v[66:69], v[188:191], 0
	v_mfma_f32_16x16x32_bf16 v[26:29], v[74:77], v[188:191], 0
	v_mfma_f32_16x16x32_bf16 v[14:17], v[66:69], v[196:199], 0
	v_mfma_f32_16x16x32_bf16 v[10:13], v[74:77], v[196:199], 0
	v_mfma_f32_16x16x32_bf16 v[62:65], v[70:73], v[176:179], v[62:65]
	v_mfma_f32_16x16x32_bf16 v[58:61], v[78:81], v[176:179], v[58:61]
	v_mfma_f32_16x16x32_bf16 v[46:49], v[70:73], v[184:187], v[46:49]
	v_mfma_f32_16x16x32_bf16 v[42:45], v[78:81], v[184:187], v[42:45]
	v_mfma_f32_16x16x32_bf16 v[30:33], v[70:73], v[192:195], v[30:33]
	v_mfma_f32_16x16x32_bf16 v[26:29], v[78:81], v[192:195], v[26:29]
	v_mfma_f32_16x16x32_bf16 v[14:17], v[70:73], v[206:209], v[14:17]
	v_mfma_f32_16x16x32_bf16 v[10:13], v[78:81], v[206:209], v[10:13]
	v_mfma_f32_16x16x32_bf16 v[54:57], v[146:149], v[162:165], 0
	v_mfma_f32_16x16x32_bf16 v[50:53], v[154:157], v[162:165], 0
	v_mfma_f32_16x16x32_bf16 v[38:41], v[146:149], v[180:183], 0
	v_mfma_f32_16x16x32_bf16 v[34:37], v[154:157], v[180:183], 0
	v_mfma_f32_16x16x32_bf16 v[22:25], v[146:149], v[188:191], 0
	v_mfma_f32_16x16x32_bf16 v[18:21], v[154:157], v[188:191], 0
	v_mfma_f32_16x16x32_bf16 v[6:9], v[146:149], v[196:199], 0
	v_mfma_f32_16x16x32_bf16 v[2:5], v[154:157], v[196:199], 0
	v_mfma_f32_16x16x32_bf16 v[54:57], v[150:153], v[176:179], v[54:57]
	v_mfma_f32_16x16x32_bf16 v[50:53], v[158:161], v[176:179], v[50:53]
	v_mfma_f32_16x16x32_bf16 v[38:41], v[150:153], v[184:187], v[38:41]
	v_mfma_f32_16x16x32_bf16 v[34:37], v[158:161], v[184:187], v[34:37]
	v_mfma_f32_16x16x32_bf16 v[22:25], v[150:153], v[192:195], v[22:25]
	v_mfma_f32_16x16x32_bf16 v[18:21], v[158:161], v[192:195], v[18:21]
	v_mfma_f32_16x16x32_bf16 v[6:9], v[150:153], v[206:209], v[6:9]
	v_mfma_f32_16x16x32_bf16 v[2:5], v[158:161], v[206:209], v[2:5]
	s_setprio 0
	s_barrier
	s_add_i32 s70, 0, 0x18000
	s_add_i32 s71, 0, 0x1c000
	v_add_u32_e32 v78, s70, v203
	v_add_u32_e32 v158, s71, v203
	ds_read_b128 v[66:69], v78
	ds_read_b128 v[70:73], v78 offset:1024
	ds_read_b128 v[74:77], v78 offset:2048
	ds_read_b128 v[78:81], v78 offset:3072
	ds_read_b128 v[146:149], v158
	ds_read_b128 v[150:153], v158 offset:1024
	ds_read_b128 v[154:157], v158 offset:2048
	ds_read_b128 v[158:161], v158 offset:3072
	s_add_u32 s6, s40, 0xb0000
	s_addc_u32 s7, s41, 0
	s_mov_b32 m0, s35
	v_lshl_add_u64 v[216:217], s[6:7], 0, v[166:167]
	ds_read_b128 v[162:165], v205 offset:32768
	ds_read_b128 v[176:179], v205 offset:33792
	ds_read_b128 v[180:183], v205 offset:34816
	ds_read_b128 v[184:187], v205 offset:35840
	ds_read_b128 v[188:191], v205 offset:36864
	ds_read_b128 v[192:195], v205 offset:37888
	ds_read_b128 v[196:199], v205 offset:38912
	ds_read_b128 v[206:209], v205 offset:39936
	global_load_lds_dwordx4 v[216:217], off
	v_lshl_add_u64 v[216:217], s[6:7], 0, v[168:169]
	s_mov_b32 m0, s46
	s_nop 0
	global_load_lds_dwordx4 v[216:217], off
	s_waitcnt vmcnt(8)
	s_waitcnt lgkmcnt(0)
	s_barrier
	s_setprio 1
	v_mfma_f32_16x16x32_bf16 v[142:145], v[66:69], v[162:165], v[142:145]
	v_mfma_f32_16x16x32_bf16 v[138:141], v[74:77], v[162:165], v[138:141]
	v_mfma_f32_16x16x32_bf16 v[126:129], v[66:69], v[180:183], v[126:129]
	v_mfma_f32_16x16x32_bf16 v[122:125], v[74:77], v[180:183], v[122:125]
	v_mfma_f32_16x16x32_bf16 v[110:113], v[66:69], v[188:191], v[110:113]
	v_mfma_f32_16x16x32_bf16 v[106:109], v[74:77], v[188:191], v[106:109]
	v_mfma_f32_16x16x32_bf16 v[94:97], v[66:69], v[196:199], v[94:97]
	v_mfma_f32_16x16x32_bf16 v[90:93], v[74:77], v[196:199], v[90:93]
	v_mfma_f32_16x16x32_bf16 v[142:145], v[70:73], v[176:179], v[142:145]
	v_mfma_f32_16x16x32_bf16 v[138:141], v[78:81], v[176:179], v[138:141]
	v_mfma_f32_16x16x32_bf16 v[126:129], v[70:73], v[184:187], v[126:129]
	v_mfma_f32_16x16x32_bf16 v[122:125], v[78:81], v[184:187], v[122:125]
	v_mfma_f32_16x16x32_bf16 v[110:113], v[70:73], v[192:195], v[110:113]
	v_mfma_f32_16x16x32_bf16 v[106:109], v[78:81], v[192:195], v[106:109]
	v_mfma_f32_16x16x32_bf16 v[94:97], v[70:73], v[206:209], v[94:97]
	v_mfma_f32_16x16x32_bf16 v[90:93], v[78:81], v[206:209], v[90:93]
	v_mfma_f32_16x16x32_bf16 v[134:137], v[146:149], v[162:165], v[134:137]
	v_mfma_f32_16x16x32_bf16 v[130:133], v[154:157], v[162:165], v[130:133]
	v_mfma_f32_16x16x32_bf16 v[118:121], v[146:149], v[180:183], v[118:121]
	v_mfma_f32_16x16x32_bf16 v[114:117], v[154:157], v[180:183], v[114:117]
	v_mfma_f32_16x16x32_bf16 v[102:105], v[146:149], v[188:191], v[102:105]
	v_mfma_f32_16x16x32_bf16 v[98:101], v[154:157], v[188:191], v[98:101]
	v_mfma_f32_16x16x32_bf16 v[86:89], v[146:149], v[196:199], v[86:89]
	v_mfma_f32_16x16x32_bf16 v[82:85], v[154:157], v[196:199], v[82:85]
	v_mfma_f32_16x16x32_bf16 v[134:137], v[150:153], v[176:179], v[134:137]
	v_mfma_f32_16x16x32_bf16 v[130:133], v[158:161], v[176:179], v[130:133]
	v_mfma_f32_16x16x32_bf16 v[118:121], v[150:153], v[184:187], v[118:121]
	v_mfma_f32_16x16x32_bf16 v[114:117], v[158:161], v[184:187], v[114:117]
	v_mfma_f32_16x16x32_bf16 v[102:105], v[150:153], v[192:195], v[102:105]
	v_mfma_f32_16x16x32_bf16 v[98:101], v[158:161], v[192:195], v[98:101]
	v_mfma_f32_16x16x32_bf16 v[86:89], v[150:153], v[206:209], v[86:89]
	v_mfma_f32_16x16x32_bf16 v[82:85], v[158:161], v[206:209], v[82:85]
	s_setprio 0
	s_barrier
	s_add_i32 s6, s70, s45
	v_lshl_add_u64 v[200:201], v[200:201], 0, s[80:81]
	s_mov_b32 m0, s6
	ds_read_b128 v[162:165], v205 offset:49152
	ds_read_b128 v[176:179], v205 offset:50176
	ds_read_b128 v[180:183], v205 offset:51200
	ds_read_b128 v[184:187], v205 offset:52224
	ds_read_b128 v[188:191], v205 offset:53248
	ds_read_b128 v[192:195], v205 offset:54272
	ds_read_b128 v[196:199], v205 offset:55296
	ds_read_b128 v[206:209], v205 offset:56320
	global_load_lds_dwordx4 v[200:201], off
	s_add_i32 m0, s6, 0x2000
	s_add_u32 s6, s38, 0xb0080
	v_lshl_add_u64 v[200:201], v[210:211], 0, s[80:81]
	s_addc_u32 s7, s39, 0
	s_add_i32 s38, s71, s45
	global_load_lds_dwordx4 v[200:201], off
	v_lshl_add_u64 v[200:201], s[6:7], 0, v[0:1]
	s_mov_b32 m0, s38
	s_nop 0
	global_load_lds_dwordx4 v[200:201], off
	v_lshl_add_u64 v[200:201], s[6:7], 0, v[170:171]
	s_add_i32 m0, s38, 0x2000
	s_nop 0
	global_load_lds_dwordx4 v[200:201], off
	v_lshl_add_u64 v[200:201], v[212:213], 0, s[80:81]
	s_mov_b32 m0, s59
	s_nop 0
	global_load_lds_dwordx4 v[200:201], off
	v_lshl_add_u64 v[200:201], v[214:215], 0, s[80:81]
	s_mov_b32 m0, s61
	s_nop 0
	global_load_lds_dwordx4 v[200:201], off
	s_waitcnt vmcnt(8)
	s_waitcnt lgkmcnt(0)
	s_barrier
	s_setprio 1
	v_mfma_f32_16x16x32_bf16 v[62:65], v[66:69], v[162:165], v[62:65]
	v_mfma_f32_16x16x32_bf16 v[58:61], v[74:77], v[162:165], v[58:61]
	v_mfma_f32_16x16x32_bf16 v[46:49], v[66:69], v[180:183], v[46:49]
	v_mfma_f32_16x16x32_bf16 v[42:45], v[74:77], v[180:183], v[42:45]
	v_mfma_f32_16x16x32_bf16 v[30:33], v[66:69], v[188:191], v[30:33]
	v_mfma_f32_16x16x32_bf16 v[26:29], v[74:77], v[188:191], v[26:29]
	v_mfma_f32_16x16x32_bf16 v[14:17], v[66:69], v[196:199], v[14:17]
	v_mfma_f32_16x16x32_bf16 v[10:13], v[74:77], v[196:199], v[10:13]
	v_mfma_f32_16x16x32_bf16 v[62:65], v[70:73], v[176:179], v[62:65]
	v_mfma_f32_16x16x32_bf16 v[58:61], v[78:81], v[176:179], v[58:61]
	v_mfma_f32_16x16x32_bf16 v[46:49], v[70:73], v[184:187], v[46:49]
	v_mfma_f32_16x16x32_bf16 v[42:45], v[78:81], v[184:187], v[42:45]
	v_mfma_f32_16x16x32_bf16 v[30:33], v[70:73], v[192:195], v[30:33]
	v_mfma_f32_16x16x32_bf16 v[26:29], v[78:81], v[192:195], v[26:29]
	v_mfma_f32_16x16x32_bf16 v[14:17], v[70:73], v[206:209], v[14:17]
	v_mfma_f32_16x16x32_bf16 v[10:13], v[78:81], v[206:209], v[10:13]
	v_mfma_f32_16x16x32_bf16 v[54:57], v[146:149], v[162:165], v[54:57]
	v_mfma_f32_16x16x32_bf16 v[50:53], v[154:157], v[162:165], v[50:53]
	v_mfma_f32_16x16x32_bf16 v[38:41], v[146:149], v[180:183], v[38:41]
	v_mfma_f32_16x16x32_bf16 v[34:37], v[154:157], v[180:183], v[34:37]
	v_mfma_f32_16x16x32_bf16 v[22:25], v[146:149], v[188:191], v[22:25]
	v_mfma_f32_16x16x32_bf16 v[18:21], v[154:157], v[188:191], v[18:21]
	v_mfma_f32_16x16x32_bf16 v[6:9], v[146:149], v[196:199], v[6:9]
	v_mfma_f32_16x16x32_bf16 v[2:5], v[154:157], v[196:199], v[2:5]
	v_mfma_f32_16x16x32_bf16 v[54:57], v[150:153], v[176:179], v[54:57]
	v_mfma_f32_16x16x32_bf16 v[50:53], v[158:161], v[176:179], v[50:53]
	v_mfma_f32_16x16x32_bf16 v[38:41], v[150:153], v[184:187], v[38:41]
	v_mfma_f32_16x16x32_bf16 v[34:37], v[158:161], v[184:187], v[34:37]
	v_mfma_f32_16x16x32_bf16 v[22:25], v[150:153], v[192:195], v[22:25]
	v_mfma_f32_16x16x32_bf16 v[18:21], v[158:161], v[192:195], v[18:21]
	v_mfma_f32_16x16x32_bf16 v[6:9], v[150:153], v[206:209], v[6:9]
	v_mfma_f32_16x16x32_bf16 v[2:5], v[158:161], v[206:209], v[2:5]
	s_setprio 0
	s_barrier
	s_add_i32 s68, s68, 2
	s_add_u32 s66, s66, 0x100
	s_addc_u32 s67, s67, 0
	s_cmp_gt_u32 s68, 41
	s_mov_b64 s[6:7], s[30:31]
